# FFN gate/up weight-transposes loops (kind 4, idle WGs beside the scan): 8 norm-scale loads issued together + LDS reads batched instead of 8 serialized load-wait round trips per item
# speedup vs baseline: 1.0047x; 1.0047x over previous
; __device__ __forceinline__ unsigned pk_bf16(float lo, float hi) { f32x2e v = {lo, hi}; bf16x2e b = __builtin_convertvector(v, bf16x2e); return __builtin_bit_cast(unsigned, b); }
; #define LAS __attribute__((address_space(3)))
; __device__ __forceinline__ void tr_item(const float* W, int Ksrc, int N, int k0, int n0, bf16* dst, int ldt, int drow0, int dcol0, LAS float* scr, int lane, const float* nscale = nullptr, const float* kscale = nullptr) {
;     f32x4 tv[8]; const int kr_ = lane >> 3, nq_ = lane & 7;
; #pragma unroll
;     for (int i = 0; i < 8; ++i) { const int kk = 8 * i + kr_; const int kr = (k0 + kk < Ksrc) ? (k0 + kk) : (Ksrc - 1); tv[i] = __builtin_nontemporal_load((const f32x4*)(W + (size_t)kr * N + n0 + 4 * nq_)); }
; #pragma unroll
;     for (int i = 0; i < 8; ++i) { const int kk = 8 * i + kr_; const bool ok = (k0 + kk < Ksrc); LAS float* d_ = scr + kk * 33 + 4 * nq_;
;         const float ks_ = (ok && kscale) ? kscale[k0 + kk] : 1.0f;
;         d_[0] = ok ? tv[i].x * ks_ : 0.f; d_[1] = ok ? tv[i].y * ks_ : 0.f; d_[2] = ok ? tv[i].z * ks_ : 0.f; d_[3] = ok ? tv[i].w * ks_ : 0.f; }
;     asm volatile("s_waitcnt lgkmcnt(0)" ::: "memory");
;     const int c = lane & 7;
; #pragma unroll
;     for (int j = 0; j < 4; ++j) { const int n = (lane >> 3) + 8 * j; const LAS float* s = scr + (8 * c) * 33 + n;
;         const float sc = nscale ? nscale[n0 + n] : 1.0f;
;         u32x4 o; o.x = pk_bf16(s[0 * 33] * sc, s[1 * 33] * sc); o.y = pk_bf16(s[2 * 33] * sc, s[3 * 33] * sc); o.z = pk_bf16(s[4 * 33] * sc, s[5 * 33] * sc); o.w = pk_bf16(s[6 * 33] * sc, s[7 * 33] * sc);
;         *(u32x4*)(dst + (size_t)(drow0 + n) * ldt + dcol0 + k0 + 8 * c) = o; }
;     asm volatile("s_waitcnt lgkmcnt(0)" ::: "memory");
; }
; __device__ __forceinline__ void tr_matrix(const float* W, int Ksrc, int N, bf16* dst, int ldt, int dcol0, int rowmode, int drow_off, LAS float* scr, int gw, int ngw, int lane, const float* nscale = nullptr, const float* kscale = nullptr) {
;     const int nkb = (Ksrc + 63) / 64, nnb = N / 32, items = nkb * nnb;
;     for (int it = gw; it < items; it += ngw) { const int kb = it / nnb, nb = it - kb * nnb, n0 = nb * 32;
;         const int drow0 = rowmode ? ((n0 >> 7) * 256 + (n0 & 127) + drow_off) : (drow_off + n0);
;         tr_item(W, Ksrc, N, kb * 64, n0, dst, ldt, drow0, dcol0, scr, lane, nscale, kscale); }
.LBB0_330:
	s_mul_hi_i32 s0, s9, 0x2e8ba2e9
	s_lshr_b32 s1, s0, 31
	s_ashr_i32 s14, s0, 5
	s_add_i32 s14, s14, s1
	s_mul_i32 s0, s14, 0xffffea00
	s_lshl_b32 s72, s14, 6
	s_add_i32 s68, s8, s0
	v_or_b32_e32 v46, s72, v32
	s_ashr_i32 s69, s68, 31
	v_lshl_add_u64 v[0:1], s[68:69], 2, v[42:43]
	s_movk_i32 s15, 0x5800
	v_min_i32_e32 v76, 0x7ff, v46
	v_mad_i64_i32 v[72:73], s[0:1], v76, s15, v[0:1]
	global_load_dwordx4 v[28:31], v[72:73], off nt
	v_or_b32_e32 v76, 8, v46
	v_min_i32_e32 v76, 0x7ff, v76
	v_mad_i64_i32 v[74:75], s[0:1], v76, s15, v[0:1]
	global_load_dwordx4 v[24:27], v[74:75], off nt
	v_or_b32_e32 v76, 16, v46
	v_min_i32_e32 v76, 0x7ff, v76
	v_mad_i64_i32 v[72:73], s[0:1], v76, s15, v[0:1]
	global_load_dwordx4 v[20:23], v[72:73], off nt
	v_or_b32_e32 v76, 24, v46
	v_min_i32_e32 v76, 0x7ff, v76
	v_mad_i64_i32 v[74:75], s[0:1], v76, s15, v[0:1]
	global_load_dwordx4 v[16:19], v[74:75], off nt
	v_or_b32_e32 v76, 32, v46
	v_min_i32_e32 v76, 0x7ff, v76
	v_mad_i64_i32 v[72:73], s[0:1], v76, s15, v[0:1]
	global_load_dwordx4 v[12:15], v[72:73], off nt
	v_or_b32_e32 v76, 40, v46
	v_min_i32_e32 v76, 0x7ff, v76
	v_mad_i64_i32 v[74:75], s[0:1], v76, s15, v[0:1]
	global_load_dwordx4 v[8:11], v[74:75], off nt
	v_or_b32_e32 v76, 48, v46
	v_min_i32_e32 v76, 0x7ff, v76
	v_mad_i64_i32 v[72:73], s[0:1], v76, s15, v[0:1]
	global_load_dwordx4 v[4:7], v[72:73], off nt
	v_or_b32_e32 v76, 56, v46
	v_min_i32_e32 v76, 0x7ff, v76
	v_mad_i64_i32 v[74:75], s[0:1], v76, s15, v[0:1]
	global_load_dwordx4 v[0:3], v[74:75], off nt
	v_ashrrev_i32_e32 v47, 31, v46
	v_lshl_add_u64 v[60:61], v[46:47], 2, s[64:65]
	v_mov_b32_e32 v62, 1.0
	v_mov_b32_e32 v63, 1.0
	v_mov_b32_e32 v64, 1.0
	v_mov_b32_e32 v65, 1.0
	v_mov_b32_e32 v66, 1.0
	v_mov_b32_e32 v67, 1.0
	v_mov_b32_e32 v68, 1.0
	v_mov_b32_e32 v69, 1.0
	s_and_saveexec_b64 s[30:31], s[66:67]
	s_cbranch_execz .Ltr_noks_g
	global_load_dword v62, v[60:61], off
	global_load_dword v63, v[60:61], off offset:32
	global_load_dword v64, v[60:61], off offset:64
	global_load_dword v65, v[60:61], off offset:96
	global_load_dword v66, v[60:61], off offset:128
	global_load_dword v67, v[60:61], off offset:160
	global_load_dword v68, v[60:61], off offset:192
	global_load_dword v69, v[60:61], off offset:224
.Ltr_noks_g:
	s_or_b64 exec, exec, s[30:31]
	v_add_u32_e32 v70, v35, v37
	s_waitcnt vmcnt(0)
	v_mul_f32_e32 v28, v28, v62
	v_mul_f32_e32 v29, v29, v62
	v_mul_f32_e32 v30, v30, v62
	v_mul_f32_e32 v31, v31, v62
	ds_write2_b32 v70, v28, v29 offset1:1
	ds_write2_b32 v70, v30, v31 offset0:2 offset1:3
	v_mul_f32_e32 v24, v24, v63
	v_mul_f32_e32 v25, v25, v63
	v_mul_f32_e32 v26, v26, v63
	v_mul_f32_e32 v27, v27, v63
	v_add_u32_e32 v71, 0x420, v70
	ds_write2_b32 v71, v24, v25 offset1:1
	ds_write2_b32 v71, v26, v27 offset0:2 offset1:3
	v_mul_f32_e32 v20, v20, v64
	v_mul_f32_e32 v21, v21, v64
	v_mul_f32_e32 v22, v22, v64
	v_mul_f32_e32 v23, v23, v64
	v_add_u32_e32 v71, 0x840, v70
	ds_write2_b32 v71, v20, v21 offset1:1
	ds_write2_b32 v71, v22, v23 offset0:2 offset1:3
	v_mul_f32_e32 v16, v16, v65
	v_mul_f32_e32 v17, v17, v65
	v_mul_f32_e32 v18, v18, v65
	v_mul_f32_e32 v19, v19, v65
	v_add_u32_e32 v71, 0xc60, v70
	ds_write2_b32 v71, v16, v17 offset1:1
	ds_write2_b32 v71, v18, v19 offset0:2 offset1:3
	v_mul_f32_e32 v12, v12, v66
	v_mul_f32_e32 v13, v13, v66
	v_mul_f32_e32 v14, v14, v66
	v_mul_f32_e32 v15, v15, v66
	v_add_u32_e32 v71, 0x1080, v70
	ds_write2_b32 v71, v12, v13 offset1:1
	ds_write2_b32 v71, v14, v15 offset0:2 offset1:3
	v_mul_f32_e32 v8, v8, v67
	v_mul_f32_e32 v9, v9, v67
	v_mul_f32_e32 v10, v10, v67
	v_mul_f32_e32 v11, v11, v67
	v_add_u32_e32 v71, 0x14a0, v70
	ds_write2_b32 v71, v8, v9 offset1:1
	ds_write2_b32 v71, v10, v11 offset0:2 offset1:3
	v_mul_f32_e32 v4, v4, v68
	v_mul_f32_e32 v5, v5, v68
	v_mul_f32_e32 v6, v6, v68
	v_mul_f32_e32 v7, v7, v68
	v_add_u32_e32 v71, 0x18c0, v70
	ds_write2_b32 v71, v4, v5 offset1:1
	ds_write2_b32 v71, v6, v7 offset0:2 offset1:3
	v_mul_f32_e32 v0, v0, v69
	v_mul_f32_e32 v1, v1, v69
	v_mul_f32_e32 v2, v2, v69
	v_mul_f32_e32 v3, v3, v69
	v_add_u32_e32 v71, 0x1ce0, v70
	ds_write2_b32 v71, v0, v1 offset1:1
	ds_write2_b32 v71, v2, v3 offset0:2 offset1:3
	s_waitcnt lgkmcnt(0)
	ds_read_b32 v0, v58
	ds_read_b32 v1, v58 offset:132
	ds_read_b32 v2, v58 offset:264
	ds_read_b32 v3, v58 offset:396
	ds_read_b32 v4, v58 offset:528
	ds_read_b32 v5, v58 offset:660
	ds_read_b32 v6, v58 offset:792
	ds_read_b32 v7, v58 offset:924
	ds_read_b32 v8, v58 offset:32
	ds_read_b32 v9, v58 offset:164
	ds_read_b32 v10, v58 offset:296
	ds_read_b32 v11, v58 offset:428
	ds_read_b32 v12, v58 offset:560
	ds_read_b32 v13, v58 offset:692
	ds_read_b32 v14, v58 offset:824
	ds_read_b32 v15, v58 offset:956
	s_mulk_i32 s14, 0xd400
	s_add_i32 s0, s7, s14
	s_and_b32 s0, s0, 0xffffff00
	s_and_b32 s1, s68, 0x60
	s_or_b32 s0, s1, s0
	s_ashr_i32 s73, s72, 31
	v_mov_b64_e32 v[70:71], s[72:73]
	v_lshl_add_u64 v[70:71], v[70:71], 1, v[44:45]
	s_waitcnt lgkmcnt(8)
	v_cvt_pk_bf16_f32 v80, v0, v1
	v_cvt_pk_bf16_f32 v81, v2, v3
	v_cvt_pk_bf16_f32 v82, v4, v5
	v_cvt_pk_bf16_f32 v83, v6, v7
	v_or_b32_e32 v60, s0, v32
	v_ashrrev_i32_e32 v61, 31, v60
	v_lshlrev_b64 v[60:61], 12, v[60:61]
	v_lshl_add_u64 v[60:61], v[70:71], 0, v[60:61]
	global_store_dwordx4 v[60:61], v[80:83], off
	ds_read_b32 v16, v58 offset:64
	ds_read_b32 v17, v58 offset:196
	ds_read_b32 v18, v58 offset:328
	ds_read_b32 v19, v58 offset:460
	ds_read_b32 v20, v58 offset:592
	ds_read_b32 v21, v58 offset:724
	ds_read_b32 v22, v58 offset:856
	ds_read_b32 v23, v58 offset:988
	s_waitcnt lgkmcnt(8)
	v_cvt_pk_bf16_f32 v84, v8, v9
	v_cvt_pk_bf16_f32 v85, v10, v11
	v_cvt_pk_bf16_f32 v86, v12, v13
	v_cvt_pk_bf16_f32 v87, v14, v15
	v_or_b32_e32 v60, s0, v48
	v_ashrrev_i32_e32 v61, 31, v60
	v_lshlrev_b64 v[60:61], 12, v[60:61]
	v_lshl_add_u64 v[60:61], v[70:71], 0, v[60:61]
	global_store_dwordx4 v[60:61], v[84:87], off
	ds_read_b32 v24, v58 offset:96
	ds_read_b32 v25, v58 offset:228
	ds_read_b32 v26, v58 offset:360
	ds_read_b32 v27, v58 offset:492
	ds_read_b32 v28, v58 offset:624
	ds_read_b32 v29, v58 offset:756
	ds_read_b32 v30, v58 offset:888
	ds_read_b32 v31, v58 offset:1020
	s_waitcnt lgkmcnt(8)
	v_cvt_pk_bf16_f32 v88, v16, v17
	v_cvt_pk_bf16_f32 v89, v18, v19
	v_cvt_pk_bf16_f32 v90, v20, v21
	v_cvt_pk_bf16_f32 v91, v22, v23
	v_or_b32_e32 v60, s0, v50
	v_ashrrev_i32_e32 v61, 31, v60
	v_lshlrev_b64 v[60:61], 12, v[60:61]
	v_lshl_add_u64 v[60:61], v[70:71], 0, v[60:61]
	global_store_dwordx4 v[60:61], v[88:91], off
	s_waitcnt lgkmcnt(0)
	v_cvt_pk_bf16_f32 v92, v24, v25
	v_cvt_pk_bf16_f32 v93, v26, v27
	v_cvt_pk_bf16_f32 v94, v28, v29
	v_cvt_pk_bf16_f32 v95, v30, v31
	v_or_b32_e32 v60, s0, v52
	v_ashrrev_i32_e32 v61, 31, v60
	v_lshlrev_b64 v[60:61], 12, v[60:61]
	v_lshl_add_u64 v[60:61], v[70:71], 0, v[60:61]
	global_store_dwordx4 v[60:61], v[92:95], off
	s_add_i32 s8, s8, s19
	s_add_i32 s7, s7, s33
	v_readlane_b32 s0, v253, 48
	s_add_i32 s9, s9, s0
	s_cmpk_lt_i32 s9, 0x1600
	s_cbranch_scc1 .LBB0_330

; __device__ __forceinline__ unsigned pk_bf16(float lo, float hi) { f32x2e v = {lo, hi}; bf16x2e b = __builtin_convertvector(v, bf16x2e); return __builtin_bit_cast(unsigned, b); }
; #define LAS __attribute__((address_space(3)))
; __device__ __forceinline__ void tr_item(const float* W, int Ksrc, int N, int k0, int n0, bf16* dst, int ldt, int drow0, int dcol0, LAS float* scr, int lane, const float* nscale = nullptr, const float* kscale = nullptr) {
;     f32x4 tv[8]; const int kr_ = lane >> 3, nq_ = lane & 7;
; #pragma unroll
;     for (int i = 0; i < 8; ++i) { const int kk = 8 * i + kr_; const int kr = (k0 + kk < Ksrc) ? (k0 + kk) : (Ksrc - 1); tv[i] = __builtin_nontemporal_load((const f32x4*)(W + (size_t)kr * N + n0 + 4 * nq_)); }
; #pragma unroll
;     for (int i = 0; i < 8; ++i) { const int kk = 8 * i + kr_; const bool ok = (k0 + kk < Ksrc); LAS float* d_ = scr + kk * 33 + 4 * nq_;
;         const float ks_ = (ok && kscale) ? kscale[k0 + kk] : 1.0f;
;         d_[0] = ok ? tv[i].x * ks_ : 0.f; d_[1] = ok ? tv[i].y * ks_ : 0.f; d_[2] = ok ? tv[i].z * ks_ : 0.f; d_[3] = ok ? tv[i].w * ks_ : 0.f; }
;     asm volatile("s_waitcnt lgkmcnt(0)" ::: "memory");
;     const int c = lane & 7;
; #pragma unroll
;     for (int j = 0; j < 4; ++j) { const int n = (lane >> 3) + 8 * j; const LAS float* s = scr + (8 * c) * 33 + n;
;         const float sc = nscale ? nscale[n0 + n] : 1.0f;
;         u32x4 o; o.x = pk_bf16(s[0 * 33] * sc, s[1 * 33] * sc); o.y = pk_bf16(s[2 * 33] * sc, s[3 * 33] * sc); o.z = pk_bf16(s[4 * 33] * sc, s[5 * 33] * sc); o.w = pk_bf16(s[6 * 33] * sc, s[7 * 33] * sc);
;         *(u32x4*)(dst + (size_t)(drow0 + n) * ldt + dcol0 + k0 + 8 * c) = o; }
;     asm volatile("s_waitcnt lgkmcnt(0)" ::: "memory");
; }
; __device__ __forceinline__ void tr_matrix(const float* W, int Ksrc, int N, bf16* dst, int ldt, int dcol0, int rowmode, int drow_off, LAS float* scr, int gw, int ngw, int lane, const float* nscale = nullptr, const float* kscale = nullptr) {
;     const int nkb = (Ksrc + 63) / 64, nnb = N / 32, items = nkb * nnb;
;     for (int it = gw; it < items; it += ngw) { const int kb = it / nnb, nb = it - kb * nnb, n0 = nb * 32;
;         const int drow0 = rowmode ? ((n0 >> 7) * 256 + (n0 & 127) + drow_off) : (drow_off + n0);
;         tr_item(W, Ksrc, N, kb * 64, n0, dst, ldt, drow0, dcol0, scr, lane, nscale, kscale); }
.LBB0_351:
	s_mul_hi_i32 s0, s9, 0x2e8ba2e9
	s_lshr_b32 s1, s0, 31
	s_ashr_i32 s14, s0, 5
	s_add_i32 s14, s14, s1
	s_mul_i32 s0, s14, 0xffffea00
	s_lshl_b32 s64, s14, 6
	s_add_i32 s42, s8, s0
	v_or_b32_e32 v44, s64, v32
	s_ashr_i32 s43, s42, 31
	v_lshl_add_u64 v[0:1], s[42:43], 2, v[42:43]
	s_movk_i32 s15, 0x5800
	v_min_i32_e32 v76, 0x7ff, v44
	v_mad_i64_i32 v[72:73], s[0:1], v76, s15, v[0:1]
	global_load_dwordx4 v[28:31], v[72:73], off nt
	v_or_b32_e32 v76, 8, v44
	v_min_i32_e32 v76, 0x7ff, v76
	v_mad_i64_i32 v[74:75], s[0:1], v76, s15, v[0:1]
	global_load_dwordx4 v[24:27], v[74:75], off nt
	v_or_b32_e32 v76, 16, v44
	v_min_i32_e32 v76, 0x7ff, v76
	v_mad_i64_i32 v[72:73], s[0:1], v76, s15, v[0:1]
	global_load_dwordx4 v[20:23], v[72:73], off nt
	v_or_b32_e32 v76, 24, v44
	v_min_i32_e32 v76, 0x7ff, v76
	v_mad_i64_i32 v[74:75], s[0:1], v76, s15, v[0:1]
	global_load_dwordx4 v[16:19], v[74:75], off nt
	v_or_b32_e32 v76, 32, v44
	v_min_i32_e32 v76, 0x7ff, v76
	v_mad_i64_i32 v[72:73], s[0:1], v76, s15, v[0:1]
	global_load_dwordx4 v[12:15], v[72:73], off nt
	v_or_b32_e32 v76, 40, v44
	v_min_i32_e32 v76, 0x7ff, v76
	v_mad_i64_i32 v[74:75], s[0:1], v76, s15, v[0:1]
	global_load_dwordx4 v[8:11], v[74:75], off nt
	v_or_b32_e32 v76, 48, v44
	v_min_i32_e32 v76, 0x7ff, v76
	v_mad_i64_i32 v[72:73], s[0:1], v76, s15, v[0:1]
	global_load_dwordx4 v[4:7], v[72:73], off nt
	v_or_b32_e32 v76, 56, v44
	v_min_i32_e32 v76, 0x7ff, v76
	v_mad_i64_i32 v[74:75], s[0:1], v76, s15, v[0:1]
	global_load_dwordx4 v[0:3], v[74:75], off nt
	v_ashrrev_i32_e32 v45, 31, v44
	v_lshl_add_u64 v[60:61], v[44:45], 2, s[62:63]
	v_mov_b32_e32 v62, 1.0
	v_mov_b32_e32 v63, 1.0
	v_mov_b32_e32 v64, 1.0
	v_mov_b32_e32 v65, 1.0
	v_mov_b32_e32 v66, 1.0
	v_mov_b32_e32 v67, 1.0
	v_mov_b32_e32 v68, 1.0
	v_mov_b32_e32 v69, 1.0
	s_and_saveexec_b64 s[30:31], s[56:57]
	s_cbranch_execz .Ltr_noks_u
	global_load_dword v62, v[60:61], off
	global_load_dword v63, v[60:61], off offset:32
	global_load_dword v64, v[60:61], off offset:64
	global_load_dword v65, v[60:61], off offset:96
	global_load_dword v66, v[60:61], off offset:128
	global_load_dword v67, v[60:61], off offset:160
	global_load_dword v68, v[60:61], off offset:192
	global_load_dword v69, v[60:61], off offset:224
.Ltr_noks_u:
	s_or_b64 exec, exec, s[30:31]
	v_add_u32_e32 v70, v35, v37
	s_waitcnt vmcnt(0)
	v_mul_f32_e32 v28, v28, v62
	v_mul_f32_e32 v29, v29, v62
	v_mul_f32_e32 v30, v30, v62
	v_mul_f32_e32 v31, v31, v62
	ds_write2_b32 v70, v28, v29 offset1:1
	ds_write2_b32 v70, v30, v31 offset0:2 offset1:3
	v_mul_f32_e32 v24, v24, v63
	v_mul_f32_e32 v25, v25, v63
	v_mul_f32_e32 v26, v26, v63
	v_mul_f32_e32 v27, v27, v63
	v_add_u32_e32 v71, 0x420, v70
	ds_write2_b32 v71, v24, v25 offset1:1
	ds_write2_b32 v71, v26, v27 offset0:2 offset1:3
	v_mul_f32_e32 v20, v20, v64
	v_mul_f32_e32 v21, v21, v64
	v_mul_f32_e32 v22, v22, v64
	v_mul_f32_e32 v23, v23, v64
	v_add_u32_e32 v71, 0x840, v70
	ds_write2_b32 v71, v20, v21 offset1:1
	ds_write2_b32 v71, v22, v23 offset0:2 offset1:3
	v_mul_f32_e32 v16, v16, v65
	v_mul_f32_e32 v17, v17, v65
	v_mul_f32_e32 v18, v18, v65
	v_mul_f32_e32 v19, v19, v65
	v_add_u32_e32 v71, 0xc60, v70
	ds_write2_b32 v71, v16, v17 offset1:1
	ds_write2_b32 v71, v18, v19 offset0:2 offset1:3
	v_mul_f32_e32 v12, v12, v66
	v_mul_f32_e32 v13, v13, v66
	v_mul_f32_e32 v14, v14, v66
	v_mul_f32_e32 v15, v15, v66
	v_add_u32_e32 v71, 0x1080, v70
	ds_write2_b32 v71, v12, v13 offset1:1
	ds_write2_b32 v71, v14, v15 offset0:2 offset1:3
	v_mul_f32_e32 v8, v8, v67
	v_mul_f32_e32 v9, v9, v67
	v_mul_f32_e32 v10, v10, v67
	v_mul_f32_e32 v11, v11, v67
	v_add_u32_e32 v71, 0x14a0, v70
	ds_write2_b32 v71, v8, v9 offset1:1
	ds_write2_b32 v71, v10, v11 offset0:2 offset1:3
	v_mul_f32_e32 v4, v4, v68
	v_mul_f32_e32 v5, v5, v68
	v_mul_f32_e32 v6, v6, v68
	v_mul_f32_e32 v7, v7, v68
	v_add_u32_e32 v71, 0x18c0, v70
	ds_write2_b32 v71, v4, v5 offset1:1
	ds_write2_b32 v71, v6, v7 offset0:2 offset1:3
	v_mul_f32_e32 v0, v0, v69
	v_mul_f32_e32 v1, v1, v69
	v_mul_f32_e32 v2, v2, v69
	v_mul_f32_e32 v3, v3, v69
	v_add_u32_e32 v71, 0x1ce0, v70
	ds_write2_b32 v71, v0, v1 offset1:1
	ds_write2_b32 v71, v2, v3 offset0:2 offset1:3
	s_waitcnt lgkmcnt(0)
	ds_read_b32 v0, v58
	ds_read_b32 v1, v58 offset:132
	ds_read_b32 v2, v58 offset:264
	ds_read_b32 v3, v58 offset:396
	ds_read_b32 v4, v58 offset:528
	ds_read_b32 v5, v58 offset:660
	ds_read_b32 v6, v58 offset:792
	ds_read_b32 v7, v58 offset:924
	ds_read_b32 v8, v58 offset:32
	ds_read_b32 v9, v58 offset:164
	ds_read_b32 v10, v58 offset:296
	ds_read_b32 v11, v58 offset:428
	ds_read_b32 v12, v58 offset:560
	ds_read_b32 v13, v58 offset:692
	ds_read_b32 v14, v58 offset:824
	ds_read_b32 v15, v58 offset:956
	s_mulk_i32 s14, 0xd400
	s_add_i32 s0, s7, s14
	s_and_b32 s0, s0, 0xffffff00
	s_and_b32 s1, s42, 0x60
	s_or_b32 s0, s1, s0
	s_bitset1_b32 s0, 7
	s_ashr_i32 s65, s64, 31
	v_mov_b64_e32 v[70:71], s[64:65]
	v_lshl_add_u64 v[70:71], v[70:71], 1, v[40:41]
	s_waitcnt lgkmcnt(8)
	v_cvt_pk_bf16_f32 v80, v0, v1
	v_cvt_pk_bf16_f32 v81, v2, v3
	v_cvt_pk_bf16_f32 v82, v4, v5
	v_cvt_pk_bf16_f32 v83, v6, v7
	v_or_b32_e32 v60, s0, v32
	v_ashrrev_i32_e32 v61, 31, v60
	v_lshlrev_b64 v[60:61], 12, v[60:61]
	v_lshl_add_u64 v[60:61], v[70:71], 0, v[60:61]
	global_store_dwordx4 v[60:61], v[80:83], off
	ds_read_b32 v16, v58 offset:64
	ds_read_b32 v17, v58 offset:196
	ds_read_b32 v18, v58 offset:328
	ds_read_b32 v19, v58 offset:460
	ds_read_b32 v20, v58 offset:592
	ds_read_b32 v21, v58 offset:724
	ds_read_b32 v22, v58 offset:856
	ds_read_b32 v23, v58 offset:988
	s_waitcnt lgkmcnt(8)
	v_cvt_pk_bf16_f32 v84, v8, v9
	v_cvt_pk_bf16_f32 v85, v10, v11
	v_cvt_pk_bf16_f32 v86, v12, v13
	v_cvt_pk_bf16_f32 v87, v14, v15
	v_or_b32_e32 v60, s0, v48
	v_ashrrev_i32_e32 v61, 31, v60
	v_lshlrev_b64 v[60:61], 12, v[60:61]
	v_lshl_add_u64 v[60:61], v[70:71], 0, v[60:61]
	global_store_dwordx4 v[60:61], v[84:87], off
	ds_read_b32 v24, v58 offset:96
	ds_read_b32 v25, v58 offset:228
	ds_read_b32 v26, v58 offset:360
	ds_read_b32 v27, v58 offset:492
	ds_read_b32 v28, v58 offset:624
	ds_read_b32 v29, v58 offset:756
	ds_read_b32 v30, v58 offset:888
	ds_read_b32 v31, v58 offset:1020
	s_waitcnt lgkmcnt(8)
	v_cvt_pk_bf16_f32 v88, v16, v17
	v_cvt_pk_bf16_f32 v89, v18, v19
	v_cvt_pk_bf16_f32 v90, v20, v21
	v_cvt_pk_bf16_f32 v91, v22, v23
	v_or_b32_e32 v60, s0, v50
	v_ashrrev_i32_e32 v61, 31, v60
	v_lshlrev_b64 v[60:61], 12, v[60:61]
	v_lshl_add_u64 v[60:61], v[70:71], 0, v[60:61]
	global_store_dwordx4 v[60:61], v[88:91], off
	s_waitcnt lgkmcnt(0)
	v_cvt_pk_bf16_f32 v92, v24, v25
	v_cvt_pk_bf16_f32 v93, v26, v27
	v_cvt_pk_bf16_f32 v94, v28, v29
	v_cvt_pk_bf16_f32 v95, v30, v31
	v_or_b32_e32 v60, s0, v52
	v_ashrrev_i32_e32 v61, 31, v60
	v_lshlrev_b64 v[60:61], 12, v[60:61]
	v_lshl_add_u64 v[60:61], v[70:71], 0, v[60:61]
	global_store_dwordx4 v[60:61], v[92:95], off
	s_add_i32 s8, s8, s19
	s_add_i32 s7, s7, s33
	v_readlane_b32 s0, v253, 48
	s_add_i32 s9, s9, s0
	s_cmpk_lt_i32 s9, 0x1600
	s_cbranch_scc1 .LBB0_351
